# on top of the s_setprio deletion: the 8 compiler-inserted s_waitcnt vmcnt(0) at the top of the attention unit loops removed (they only waited for the previous unit's output stores before issuing the Q
# baseline (speedup 1.0000x reference)
.LBB0_495:
	s_and_b64 s[0:1], s[6:7], exec
	s_cselect_b32 s4, s65, s66
	s_lshl_b32 s0, s4, 8
	s_or_b32 s38, s36, s0
	s_mul_hi_u32 s2, s38, 0x2800
	s_mul_i32 s1, s38, 0x2800
	s_add_i32 s3, s2, s75
	v_mbcnt_lo_u32_b32 v0, -1, 0
	v_mbcnt_hi_u32_b32 v0, -1, v0
	s_add_u32 s2, s67, s1
	v_or_b32_e32 v2, s33, v0
	s_addc_u32 s3, s68, s3
	v_ashrrev_i32_e32 v149, 6, v2
	v_and_b32_e32 v16, 31, v2
	v_lshlrev_b32_e32 v17, 5, v149
	v_bfe_u32 v3, v2, 5, 1
	v_or_b32_e32 v0, v17, v16
	v_mov_b64_e32 v[4:5], s[2:3]
	v_mad_i64_i32 v[4:5], s[2:3], v0, s17, v[4:5]
	v_lshlrev_b32_e32 v0, 4, v3
	v_lshl_add_u64 v[4:5], v[4:5], 0, v[0:1]
	global_load_dwordx4 v[112:115], v[4:5], off
	global_load_dwordx4 v[116:119], v[4:5], off offset:32
	global_load_dwordx4 v[120:123], v[4:5], off offset:64
	global_load_dwordx4 v[124:127], v[4:5], off offset:96
	global_load_dwordx4 v[128:131], v[4:5], off offset:128
	global_load_dwordx4 v[132:135], v[4:5], off offset:160
	global_load_dwordx4 v[136:139], v[4:5], off offset:192
	global_load_dwordx4 v[140:143], v[4:5], off offset:224
	v_and_b32_e32 v0, 15, v2
	v_lshlrev_b32_e32 v4, 8, v16
	v_bitop3_b32 v5, v3, v2, 15 bitop3:0x78
	v_lshl_or_b32 v150, v5, 4, v4
	v_bitop3_b32 v5, v3, v0, 2 bitop3:0x36
	v_lshl_or_b32 v151, v5, 4, v4
	v_bitop3_b32 v5, v3, v0, 4 bitop3:0x36
	v_lshl_or_b32 v152, v5, 4, v4
	v_bitop3_b32 v5, v3, v0, 6 bitop3:0x36
	v_lshl_or_b32 v153, v5, 4, v4
	v_bitop3_b32 v5, v3, v0, 8 bitop3:0x36
	v_lshl_or_b32 v154, v5, 4, v4
	v_bitop3_b32 v5, v3, v0, 10 bitop3:0x36
	v_and_b32_e32 v18, 63, v2
	v_lshl_or_b32 v155, v5, 4, v4
	v_bitop3_b32 v5, v3, v0, 12 bitop3:0x36
	v_bitop3_b32 v0, v3, v0, 14 bitop3:0x36
	v_readfirstlane_b32 s1, v2
	v_lshlrev_b32_e32 v19, 2, v149
	v_lshl_or_b32 v156, v5, 4, v4
	v_lshl_or_b32 v157, v0, 4, v4
	v_cmp_gt_u32_e32 vcc, 2, v18
	s_and_saveexec_b64 s[2:3], vcc
	s_cbranch_execz .LBB0_497
	v_lshlrev_b32_e32 v0, 5, v18
	v_add3_u32 v0, v19, s24, v0
	ds_write_b32 v0, v1

.LBB0_563:
	s_ashr_i32 s0, s49, 5
	s_ashr_i32 s1, s0, 31
	s_lshl_b64 s[6:7], s[0:1], 11
	s_and_b32 s1, s24, 0x700
	s_or_b32 s6, s6, s1
	s_mul_i32 s1, s7, 0x2800
	s_mul_hi_u32 s2, s6, 0x2800
	s_add_i32 s2, s2, s1
	s_mul_i32 s1, s6, 0x2800
	s_add_u32 s1, s30, s1
	s_addc_u32 s2, s31, s2
	s_and_b32 s3, s16, 0x180
	s_lshl_b32 s50, s3, 1
	s_add_u32 s1, s1, s50
	s_addc_u32 s3, s2, 0
	s_add_u32 s2, s1, 0x2400
	s_addc_u32 s3, s3, 0
	s_lshl_b32 s0, s0, 8
	s_ashr_i32 s1, s0, 31
	s_lshl_b64 s[0:1], s[0:1], 13
	s_add_u32 s0, s34, s0
	v_mbcnt_lo_u32_b32 v0, -1, 0
	v_mbcnt_hi_u32_b32 v0, -1, v0
	s_addc_u32 s1, s35, s1
	v_or_b32_e32 v2, s33, v0
	s_add_u32 s8, s0, s50
	v_ashrrev_i32_e32 v3, 6, v2
	v_and_b32_e32 v4, 31, v2
	v_and_b32_e32 v32, 63, v2
	v_lshl_or_b32 v6, v3, 5, v4
	v_mov_b64_e32 v[0:1], s[2:3]
	s_addc_u32 s9, s1, 0
	v_mad_i64_i32 v[0:1], s[0:1], v6, s26, v[0:1]
	v_lshlrev_b32_e32 v6, 11, v3
	v_lshlrev_b32_e32 v33, 4, v32
	v_or_b32_e32 v8, v33, v6
	v_ashrrev_i32_e32 v8, 8, v8
	v_lshlrev_b32_e32 v3, 2, v3
	v_xor_b32_e32 v9, v8, v2
	v_and_b32_e32 v10, 3, v8
	v_lshrrev_b32_e32 v8, 1, v8
	v_and_b32_e32 v7, 0x7ffffff0, v3
	v_and_b32_e32 v8, 12, v8
	v_lshlrev_b32_e32 v9, 4, v9
	v_or3_b32 v8, v10, v8, v7
	v_and_b32_e32 v9, 0xf0, v9
	v_lshl_or_b32 v165, v8, 13, v9
	v_or_b32_e32 v8, 0x400, v33
	v_or_b32_e32 v6, v8, v6
	v_ashrrev_i32_e32 v6, 8, v6
	v_xor_b32_e32 v9, v6, v2
	v_and_b32_e32 v10, 3, v6
	v_lshrrev_b32_e32 v6, 1, v6
	v_and_b32_e32 v6, 12, v6
	v_lshlrev_b32_e32 v9, 4, v9
	v_bfe_u32 v5, v2, 5, 1
	v_or3_b32 v6, v10, v6, v7
	v_and_b32_e32 v9, 0xf0, v9
	v_lshlrev_b32_e32 v144, 4, v5
	v_lshl_or_b32 v6, v6, 13, v9
	v_lshl_add_u64 v[0:1], v[0:1], 0, v[144:145]
	v_add_u32_e32 v166, 0x40000, v6
	v_and_b32_e32 v6, 15, v2
	v_lshlrev_b32_e32 v4, 8, v4
	global_load_dwordx4 v[140:143], v[0:1], off
	global_load_dwordx4 v[136:139], v[0:1], off offset:32
	global_load_dwordx4 v[132:135], v[0:1], off offset:64
	global_load_dwordx4 v[128:131], v[0:1], off offset:96
	global_load_dwordx4 v[124:127], v[0:1], off offset:128
	global_load_dwordx4 v[120:123], v[0:1], off offset:160
	global_load_dwordx4 v[116:119], v[0:1], off offset:192
	global_load_dwordx4 v[112:115], v[0:1], off offset:224
	v_bitop3_b32 v0, v5, v6, 2 bitop3:0x36
	v_lshl_or_b32 v93, v0, 4, v4
	v_bitop3_b32 v0, v5, v6, 4 bitop3:0x36
	v_lshl_or_b32 v94, v0, 4, v4
	v_bitop3_b32 v0, v5, v6, 6 bitop3:0x36
	v_lshl_or_b32 v95, v0, 4, v4
	v_bitop3_b32 v0, v5, v6, 8 bitop3:0x36
	v_lshl_or_b32 v96, v0, 4, v4
	v_bitop3_b32 v0, v5, v6, 10 bitop3:0x36
	v_lshl_or_b32 v97, v0, 4, v4
	v_bitop3_b32 v0, v5, v6, 12 bitop3:0x36
	v_bitop3_b32 v9, v5, v2, 15 bitop3:0x78
	v_lshl_or_b32 v155, v0, 4, v4
	v_bitop3_b32 v0, v5, v6, 14 bitop3:0x36
	s_mov_b32 m0, s56
	v_lshl_or_b32 v92, v9, 4, v4
	v_lshl_or_b32 v156, v0, 4, v4
	s_waitcnt lgkmcnt(0)
	s_barrier
	v_and_b32_e32 v1, 12, v3
	global_load_lds_dwordx4 v165, s[8:9]
	s_mov_b32 m0, s38
	v_lshlrev_b32_e32 v3, 1, v2
	global_load_lds_dwordx4 v166, s[8:9]
	v_and_b32_e32 v3, 32, v3
	v_lshlrev_b32_e32 v35, 3, v32
	v_bfe_u32 v0, v2, 2, 2
	v_add_u32_e32 v3, v3, v7
	v_and_b32_e32 v34, 24, v35
	v_or3_b32 v0, v0, v1, v3
	v_lshl_or_b32 v0, v0, 12, v34
	s_add_u32 s2, s8, 0x400
	v_readfirstlane_b32 s0, v2
	v_and_or_b32 v1, v2, 32, v0
	s_waitcnt vmcnt(0)
	s_addc_u32 s3, s9, 0
	v_lshlrev_b32_e32 v146, 1, v1
	v_lshrrev_b32_e32 v1, 4, v8
	s_waitcnt lgkmcnt(0)
	s_barrier
	s_and_b32 s1, s0, 0xffffff00
	v_and_or_b32 v0, v1, s27, v0
	s_cmpk_eq_i32 s1, 0x100
	v_lshlrev_b32_e32 v144, 1, v0
	s_cselect_b64 s[4:5], -1, 0
	s_cmpk_lg_i32 s1, 0x100
	s_waitcnt vmcnt(0)
	s_cbranch_scc1 .LBB0_565
	s_add_u32 s20, s8, 0x80000
	s_addc_u32 s21, s9, 0
	s_mov_b32 m0, s39
	s_nop 0
	global_load_lds_dwordx4 v165, s[20:21]
	s_mov_b32 m0, s40
	s_nop 0
	global_load_lds_dwordx4 v166, s[20:21]
	s_mov_b32 m0, s41
	s_nop 0
	global_load_lds_dwordx4 v146, s[2:3]
	s_mov_b32 m0, s42
	s_nop 0
	global_load_lds_dwordx4 v144, s[2:3]
	s_waitcnt lgkmcnt(0)
	s_barrier

.LBB0_1075:
	s_and_b64 s[0:1], s[6:7], exec
	s_cselect_b32 s4, s63, s64
	s_lshl_b32 s0, s4, 8
	s_or_b32 s36, s34, s0
	s_mul_hi_u32 s2, s36, 0x2800
	s_mul_i32 s1, s36, 0x2800
	s_add_i32 s3, s2, s73
	v_mbcnt_lo_u32_b32 v0, -1, 0
	v_mbcnt_hi_u32_b32 v0, -1, v0
	s_add_u32 s2, s65, s1
	v_or_b32_e32 v2, s33, v0
	s_addc_u32 s3, s66, s3
	v_ashrrev_i32_e32 v149, 6, v2
	v_and_b32_e32 v16, 31, v2
	v_lshlrev_b32_e32 v17, 5, v149
	v_bfe_u32 v3, v2, 5, 1
	v_or_b32_e32 v0, v17, v16
	v_mov_b64_e32 v[4:5], s[2:3]
	v_mad_i64_i32 v[4:5], s[2:3], v0, s17, v[4:5]
	v_lshlrev_b32_e32 v0, 4, v3
	v_lshl_add_u64 v[4:5], v[4:5], 0, v[0:1]
	global_load_dwordx4 v[112:115], v[4:5], off
	global_load_dwordx4 v[116:119], v[4:5], off offset:32
	global_load_dwordx4 v[120:123], v[4:5], off offset:64
	global_load_dwordx4 v[124:127], v[4:5], off offset:96
	global_load_dwordx4 v[128:131], v[4:5], off offset:128
	global_load_dwordx4 v[132:135], v[4:5], off offset:160
	global_load_dwordx4 v[136:139], v[4:5], off offset:192
	global_load_dwordx4 v[140:143], v[4:5], off offset:224
	v_and_b32_e32 v0, 15, v2
	v_lshlrev_b32_e32 v4, 8, v16
	v_bitop3_b32 v5, v3, v2, 15 bitop3:0x78
	v_lshl_or_b32 v150, v5, 4, v4
	v_bitop3_b32 v5, v3, v0, 2 bitop3:0x36
	v_lshl_or_b32 v151, v5, 4, v4
	v_bitop3_b32 v5, v3, v0, 4 bitop3:0x36
	v_lshl_or_b32 v152, v5, 4, v4
	v_bitop3_b32 v5, v3, v0, 6 bitop3:0x36
	v_lshl_or_b32 v153, v5, 4, v4
	v_bitop3_b32 v5, v3, v0, 8 bitop3:0x36
	v_lshl_or_b32 v154, v5, 4, v4
	v_bitop3_b32 v5, v3, v0, 10 bitop3:0x36
	v_and_b32_e32 v18, 63, v2
	v_lshl_or_b32 v155, v5, 4, v4
	v_bitop3_b32 v5, v3, v0, 12 bitop3:0x36
	v_bitop3_b32 v0, v3, v0, 14 bitop3:0x36
	v_readfirstlane_b32 s1, v2
	v_lshlrev_b32_e32 v19, 2, v149
	v_lshl_or_b32 v156, v5, 4, v4
	v_lshl_or_b32 v157, v0, 4, v4
	v_cmp_gt_u32_e32 vcc, 2, v18
	s_and_saveexec_b64 s[2:3], vcc
	s_cbranch_execz .LBB0_1077
	v_lshlrev_b32_e32 v0, 5, v18
	v_add3_u32 v0, v19, s24, v0
	ds_write_b32 v0, v1

.LBB0_1143:
	s_ashr_i32 s0, s47, 5
	s_ashr_i32 s1, s0, 31
	s_lshl_b64 s[6:7], s[0:1], 11
	s_and_b32 s1, s24, 0x700
	s_or_b32 s6, s6, s1
	s_mul_i32 s1, s7, 0x2800
	s_mul_hi_u32 s2, s6, 0x2800
	s_add_i32 s2, s2, s1
	s_mul_i32 s1, s6, 0x2800
	s_add_u32 s1, s30, s1
	s_addc_u32 s2, s31, s2
	s_and_b32 s3, s16, 0x180
	s_lshl_b32 s48, s3, 1
	s_add_u32 s1, s1, s48
	s_addc_u32 s3, s2, 0
	s_add_u32 s2, s1, 0x2400
	s_addc_u32 s3, s3, 0
	s_lshl_b32 s0, s0, 8
	s_ashr_i32 s1, s0, 31
	s_lshl_b64 s[0:1], s[0:1], 13
	s_add_u32 s0, s22, s0
	v_mbcnt_lo_u32_b32 v0, -1, 0
	v_mbcnt_hi_u32_b32 v0, -1, v0
	s_addc_u32 s1, s23, s1
	v_or_b32_e32 v2, s33, v0
	s_add_u32 s4, s0, s48
	v_ashrrev_i32_e32 v3, 6, v2
	v_and_b32_e32 v4, 31, v2
	v_and_b32_e32 v32, 63, v2
	v_lshl_or_b32 v6, v3, 5, v4
	v_mov_b64_e32 v[0:1], s[2:3]
	s_addc_u32 s5, s1, 0
	v_mad_i64_i32 v[0:1], s[0:1], v6, s26, v[0:1]
	v_lshlrev_b32_e32 v6, 11, v3
	v_lshlrev_b32_e32 v33, 4, v32
	v_or_b32_e32 v8, v33, v6
	v_ashrrev_i32_e32 v8, 8, v8
	v_lshlrev_b32_e32 v3, 2, v3
	v_xor_b32_e32 v9, v8, v2
	v_and_b32_e32 v10, 3, v8
	v_lshrrev_b32_e32 v8, 1, v8
	v_and_b32_e32 v7, 0x7ffffff0, v3
	v_and_b32_e32 v8, 12, v8
	v_lshlrev_b32_e32 v9, 4, v9
	v_or3_b32 v8, v10, v8, v7
	v_and_b32_e32 v9, 0xf0, v9
	v_lshl_or_b32 v165, v8, 13, v9
	v_or_b32_e32 v8, 0x400, v33
	v_or_b32_e32 v6, v8, v6
	v_ashrrev_i32_e32 v6, 8, v6
	v_xor_b32_e32 v9, v6, v2
	v_and_b32_e32 v10, 3, v6
	v_lshrrev_b32_e32 v6, 1, v6
	v_and_b32_e32 v6, 12, v6
	v_lshlrev_b32_e32 v9, 4, v9
	v_bfe_u32 v5, v2, 5, 1
	v_or3_b32 v6, v10, v6, v7
	v_and_b32_e32 v9, 0xf0, v9
	v_lshlrev_b32_e32 v144, 4, v5
	v_lshl_or_b32 v6, v6, 13, v9
	v_lshl_add_u64 v[0:1], v[0:1], 0, v[144:145]
	v_add_u32_e32 v166, 0x40000, v6
	v_and_b32_e32 v6, 15, v2
	v_lshlrev_b32_e32 v4, 8, v4
	global_load_dwordx4 v[140:143], v[0:1], off
	global_load_dwordx4 v[136:139], v[0:1], off offset:32
	global_load_dwordx4 v[132:135], v[0:1], off offset:64
	global_load_dwordx4 v[128:131], v[0:1], off offset:96
	global_load_dwordx4 v[124:127], v[0:1], off offset:128
	global_load_dwordx4 v[120:123], v[0:1], off offset:160
	global_load_dwordx4 v[116:119], v[0:1], off offset:192
	global_load_dwordx4 v[112:115], v[0:1], off offset:224
	v_bitop3_b32 v0, v5, v6, 2 bitop3:0x36
	v_lshl_or_b32 v93, v0, 4, v4
	v_bitop3_b32 v0, v5, v6, 4 bitop3:0x36
	v_lshl_or_b32 v94, v0, 4, v4
	v_bitop3_b32 v0, v5, v6, 6 bitop3:0x36
	v_lshl_or_b32 v95, v0, 4, v4
	v_bitop3_b32 v0, v5, v6, 8 bitop3:0x36
	v_lshl_or_b32 v96, v0, 4, v4
	v_bitop3_b32 v0, v5, v6, 10 bitop3:0x36
	v_lshl_or_b32 v97, v0, 4, v4
	v_bitop3_b32 v0, v5, v6, 12 bitop3:0x36
	s_add_u32 s8, s4, 0x15400800
	v_bitop3_b32 v9, v5, v2, 15 bitop3:0x78
	v_lshl_or_b32 v155, v0, 4, v4
	v_bitop3_b32 v0, v5, v6, 14 bitop3:0x36
	s_mov_b32 m0, s54
	s_addc_u32 s9, s5, 0
	v_lshl_or_b32 v92, v9, 4, v4
	v_lshl_or_b32 v156, v0, 4, v4
	s_waitcnt lgkmcnt(0)
	s_barrier
	v_and_b32_e32 v1, 12, v3
	global_load_lds_dwordx4 v165, s[8:9]
	s_mov_b32 m0, s36
	v_lshlrev_b32_e32 v3, 1, v2
	global_load_lds_dwordx4 v166, s[8:9]
	v_and_b32_e32 v3, 32, v3
	v_lshlrev_b32_e32 v35, 3, v32
	v_bfe_u32 v0, v2, 2, 2
	v_add_u32_e32 v3, v3, v7
	v_and_b32_e32 v34, 24, v35
	v_or3_b32 v0, v0, v1, v3
	v_lshl_or_b32 v0, v0, 12, v34
	s_add_u32 s2, s4, 0x15400c00
	v_readfirstlane_b32 s0, v2
	v_and_or_b32 v1, v2, 32, v0
	s_waitcnt vmcnt(0)
	s_addc_u32 s3, s5, 0
	v_lshlrev_b32_e32 v146, 1, v1
	v_lshrrev_b32_e32 v1, 4, v8
	s_waitcnt lgkmcnt(0)
	s_barrier
	s_and_b32 s1, s0, 0xffffff00
	v_and_or_b32 v0, v1, s27, v0
	s_cmpk_eq_i32 s1, 0x100
	v_lshlrev_b32_e32 v144, 1, v0
	s_cselect_b64 s[4:5], -1, 0
	s_cmpk_lg_i32 s1, 0x100
	s_waitcnt vmcnt(0)
	s_cbranch_scc1 .LBB0_1145
	s_add_u32 s20, s8, 0x80000
	s_addc_u32 s21, s9, 0
	s_mov_b32 m0, s37
	s_nop 0
	global_load_lds_dwordx4 v165, s[20:21]
	s_mov_b32 m0, s38
	s_nop 0
	global_load_lds_dwordx4 v166, s[20:21]
	s_mov_b32 m0, s39
	s_nop 0
	global_load_lds_dwordx4 v146, s[2:3]
	s_mov_b32 m0, s40
	s_nop 0
	global_load_lds_dwordx4 v144, s[2:3]
	s_waitcnt lgkmcnt(0)
	s_barrier

.LBB0_1842:
	s_and_b64 s[2:3], s[4:5], exec
	s_cselect_b32 s12, s95, s96
	s_lshl_b32 s1, s12, 8
	s_or_b32 s56, s42, s1
	s_mul_hi_u32 s3, s56, 0x1200
	s_mul_i32 s6, s43, 0x1200
	s_mul_i32 s2, s56, 0x1200
	s_add_i32 s3, s3, s6
	v_mbcnt_lo_u32_b32 v0, -1, 0
	v_mbcnt_hi_u32_b32 v0, -1, v0
	s_add_u32 s2, s97, s2
	v_or_b32_e32 v4, s33, v0
	s_addc_u32 s3, s16, s3
	v_ashrrev_i32_e32 v5, 6, v4
	v_and_b32_e32 v32, 31, v4
	v_lshlrev_b32_e32 v33, 5, v5
	v_bfe_u32 v6, v4, 5, 1
	v_or_b32_e32 v0, v33, v32
	v_mov_b64_e32 v[2:3], s[2:3]
	s_movk_i32 s2, 0x1200
	v_and_b32_e32 v34, 63, v4
	v_mad_i64_i32 v[2:3], s[2:3], v0, s2, v[2:3]
	v_lshlrev_b32_e32 v0, 4, v6
	v_lshl_add_u64 v[2:3], v[2:3], 0, v[0:1]
	v_lshlrev_b32_e32 v0, 11, v5
	v_lshlrev_b32_e32 v35, 4, v34
	v_or_b32_e32 v9, v35, v0
	v_ashrrev_i32_e32 v9, 8, v9
	v_lshlrev_b32_e32 v7, 2, v5
	v_xor_b32_e32 v10, v9, v4
	v_and_b32_e32 v11, 3, v9
	v_lshrrev_b32_e32 v9, 1, v9
	v_and_b32_e32 v8, 0x7ffffff0, v7
	v_and_b32_e32 v9, 12, v9
	v_or3_b32 v9, v11, v9, v8
	v_mul_lo_u32 v9, v9, s73
	v_lshlrev_b32_e32 v10, 3, v10
	v_and_or_b32 v9, v10, s74, v9
	v_lshlrev_b32_e32 v184, 1, v9
	v_or_b32_e32 v9, 0x400, v35
	v_or_b32_e32 v0, v9, v0
	v_ashrrev_i32_e32 v0, 8, v0
	v_xor_b32_e32 v10, v0, v4
	v_and_b32_e32 v11, 3, v0
	v_lshrrev_b32_e32 v0, 1, v0
	v_and_b32_e32 v0, 12, v0
	v_or3_b32 v0, v11, v0, v8
	v_mul_lo_u32 v0, v0, s73
	v_lshlrev_b32_e32 v10, 3, v10
	v_and_or_b32 v0, v10, s74, v0
	v_lshl_add_u32 v185, v0, 1, v176
	v_lshl_or_b32 v0, v5, 10, v35
	v_ashrrev_i32_e32 v5, 7, v0
	v_lshrrev_b32_e32 v0, 8, v0
	v_and_b32_e32 v10, 3, v5
	v_lshrrev_b32_e32 v11, 1, v5
	v_lshlrev_b32_e32 v5, 3, v5
	v_xor_b32_e32 v0, v0, v4
	v_and_b32_e32 v5, 32, v5
	v_and_b32_e32 v11, 12, v11
	v_add_u32_e32 v5, v5, v8
	v_lshlrev_b32_e32 v0, 4, v0
	v_or3_b32 v5, v10, v11, v5
	v_and_b32_e32 v0, 0x70, v0
	v_lshl_or_b32 v186, v5, 7, v0
	v_and_b32_e32 v0, 15, v4
	v_lshlrev_b32_e32 v12, 8, v32
	global_load_dwordx4 v[172:175], v[2:3], off
	global_load_dwordx4 v[168:171], v[2:3], off offset:32
	global_load_dwordx4 v[164:167], v[2:3], off offset:64
	global_load_dwordx4 v[160:163], v[2:3], off offset:96
	global_load_dwordx4 v[156:159], v[2:3], off offset:128
	global_load_dwordx4 v[152:155], v[2:3], off offset:160
	global_load_dwordx4 v[148:151], v[2:3], off offset:192
	global_load_dwordx4 v[144:147], v[2:3], off offset:224
	global_load_dwordx4 v[140:143], v[2:3], off offset:256
	global_load_dwordx4 v[136:139], v[2:3], off offset:288
	global_load_dwordx4 v[132:135], v[2:3], off offset:320
	global_load_dwordx4 v[128:131], v[2:3], off offset:352
	v_bitop3_b32 v2, v6, v0, 2 bitop3:0x36
	v_lshl_or_b32 v200, v2, 4, v12
	v_bitop3_b32 v2, v6, v0, 4 bitop3:0x36
	v_lshl_or_b32 v201, v2, 4, v12
	v_bitop3_b32 v2, v6, v0, 6 bitop3:0x36
	v_lshl_or_b32 v202, v2, 4, v12
	v_bitop3_b32 v2, v6, v0, 8 bitop3:0x36
	v_lshl_or_b32 v197, v2, 4, v12
	v_bitop3_b32 v2, v6, v0, 10 bitop3:0x36
	v_lshrrev_b32_e32 v5, 1, v4
	v_lshl_or_b32 v198, v2, 4, v12
	v_bitop3_b32 v2, v6, v0, 12 bitop3:0x36
	v_bitop3_b32 v0, v6, v0, 14 bitop3:0x36
	v_bfe_u32 v10, v4, 1, 3
	v_lshl_or_b32 v11, v32, 7, v177
	v_lshl_or_b32 v196, v0, 4, v12
	v_bitop3_b32 v0, v6, v5, 7 bitop3:0x78
	v_lshl_or_b32 v192, v0, 4, v11
	v_bitop3_b32 v0, v6, v10, 2 bitop3:0x36
	v_lshl_or_b32 v193, v0, 4, v11
	v_bitop3_b32 v0, v6, v10, 4 bitop3:0x36
	v_bitop3_b32 v13, v6, v4, 15 bitop3:0x78
	v_lshl_or_b32 v190, v0, 4, v11
	v_bitop3_b32 v0, v6, v10, 6 bitop3:0x36
	s_mov_b32 m0, s68
	v_lshl_or_b32 v199, v13, 4, v12
	v_lshl_or_b32 v195, v2, 4, v12
	v_lshl_or_b32 v191, v0, 4, v11
	v_readfirstlane_b32 s3, v179
	v_readfirstlane_b32 s2, v180
	s_waitcnt lgkmcnt(0)
	s_barrier
	v_lshlrev_b32_e32 v3, 1, v4
	s_nop 2
	global_load_lds_dwordx4 v184, s[2:3]
	s_mov_b32 m0, s93
	v_and_b32_e32 v3, 32, v3
	global_load_lds_dwordx4 v185, s[2:3]
	v_readfirstlane_b32 s3, v181
	v_readfirstlane_b32 s2, v182
	s_add_i32 m0, s71, 0x4000
	v_bfe_u32 v0, v4, 2, 2
	v_and_b32_e32 v2, 12, v7
	v_add_u32_e32 v3, v3, v8
	s_nop 0
	global_load_lds_dwordx4 v186, s[2:3]
	v_lshlrev_b32_e32 v37, 3, v34
	v_or3_b32 v0, v0, v2, v3
	v_and_b32_e32 v36, 24, v37
	v_mul_lo_u32 v0, v0, s73
	v_or_b32_e32 v0, v0, v36
	v_and_b32_e32 v187, 32, v4
	v_or_b32_e32 v2, v0, v187
	v_readfirstlane_b32 s2, v4
	v_lshlrev_b32_e32 v189, 1, v2
	v_lshrrev_b32_e32 v2, 4, v9
	s_movk_i32 s3, 0x60
	s_waitcnt vmcnt(0)
	v_and_or_b32 v0, v2, s3, v0
	s_waitcnt lgkmcnt(0)
	s_barrier
	s_and_b32 s3, s2, 0xffffff00
	s_cmpk_eq_i32 s3, 0x100
	v_lshlrev_b32_e32 v188, 1, v0
	s_cselect_b64 s[60:61], -1, 0
	s_cmpk_lg_i32 s3, 0x100
	s_waitcnt vmcnt(0)
	s_cbranch_scc1 .LBB0_1844
	s_mov_b32 m0, s75
	s_nop 0
	global_load_lds_dwordx4 v184, s[46:47]
	s_mov_b32 m0, s76
	s_nop 0
	global_load_lds_dwordx4 v185, s[46:47]
	s_mov_b32 m0, s77
	s_nop 0
	global_load_lds_dwordx4 v186, s[48:49]
	s_mov_b32 m0, s88
	s_nop 0
	global_load_lds_dwordx4 v189, s[44:45]
	s_mov_b32 m0, s89
	s_nop 0
	global_load_lds_dwordx4 v188, s[44:45]
	s_waitcnt lgkmcnt(0)
	s_barrier

.LBB0_1914:
	s_ashr_i32 s2, s57, 5
	s_ashr_i32 s3, s2, 31
	s_lshl_b64 s[6:7], s[2:3], 11
	s_and_b32 s1, s24, 0x700
	s_or_b32 s6, s6, s1
	s_mul_i32 s1, s7, 0xe00
	s_mul_hi_u32 s3, s6, 0xe00
	s_add_i32 s3, s3, s1
	s_mul_i32 s1, s6, 0xe00
	s_add_u32 s1, s30, s1
	s_addc_u32 s3, s31, s3
	s_and_b32 s4, s16, 0x180
	s_lshl_b32 s58, s4, 1
	s_add_u32 s4, s1, s58
	s_addc_u32 s5, s3, 0
	s_lshl_b32 s2, s2, 8
	s_ashr_i32 s3, s2, 31
	s_lshl_b64 s[2:3], s[2:3], 13
	s_add_u32 s1, s22, s2
	v_mbcnt_lo_u32_b32 v0, -1, 0
	v_mbcnt_hi_u32_b32 v0, -1, v0
	s_addc_u32 s2, s23, s3
	v_or_b32_e32 v2, s33, v0
	s_add_u32 s1, s1, s58
	v_ashrrev_i32_e32 v3, 6, v2
	v_and_b32_e32 v4, 31, v2
	v_and_b32_e32 v32, 63, v2
	v_lshl_or_b32 v6, v3, 5, v4
	s_waitcnt lgkmcnt(0)
	v_mov_b64_e32 v[0:1], s[4:5]
	s_addc_u32 s12, s2, 0
	v_mad_i64_i32 v[0:1], s[2:3], v6, s26, v[0:1]
	v_lshlrev_b32_e32 v6, 11, v3
	v_lshlrev_b32_e32 v33, 4, v32
	v_or_b32_e32 v8, v33, v6
	v_ashrrev_i32_e32 v8, 8, v8
	v_lshlrev_b32_e32 v3, 2, v3
	v_xor_b32_e32 v9, v8, v2
	v_and_b32_e32 v10, 3, v8
	v_lshrrev_b32_e32 v8, 1, v8
	v_and_b32_e32 v7, 0x7ffffff0, v3
	v_and_b32_e32 v8, 12, v8
	v_lshlrev_b32_e32 v9, 4, v9
	v_or3_b32 v8, v10, v8, v7
	v_and_b32_e32 v9, 0xf0, v9
	v_lshl_or_b32 v165, v8, 13, v9
	v_or_b32_e32 v8, 0x400, v33
	v_or_b32_e32 v6, v8, v6
	v_ashrrev_i32_e32 v6, 8, v6
	v_xor_b32_e32 v9, v6, v2
	v_and_b32_e32 v10, 3, v6
	v_lshrrev_b32_e32 v6, 1, v6
	v_and_b32_e32 v6, 12, v6
	v_lshlrev_b32_e32 v9, 4, v9
	v_bfe_u32 v5, v2, 5, 1
	v_or3_b32 v6, v10, v6, v7
	v_and_b32_e32 v9, 0xf0, v9
	v_lshlrev_b32_e32 v144, 4, v5
	v_lshl_or_b32 v6, v6, 13, v9
	v_lshl_add_u64 v[0:1], v[0:1], 0, v[144:145]
	v_add_u32_e32 v166, 0x40000, v6
	v_and_b32_e32 v6, 15, v2
	v_lshlrev_b32_e32 v4, 8, v4
	global_load_dwordx4 v[140:143], v[0:1], off offset:1024
	global_load_dwordx4 v[136:139], v[0:1], off offset:1056
	global_load_dwordx4 v[132:135], v[0:1], off offset:1088
	global_load_dwordx4 v[128:131], v[0:1], off offset:1120
	global_load_dwordx4 v[124:127], v[0:1], off offset:1152
	global_load_dwordx4 v[120:123], v[0:1], off offset:1184
	global_load_dwordx4 v[116:119], v[0:1], off offset:1216
	global_load_dwordx4 v[112:115], v[0:1], off offset:1248
	v_bitop3_b32 v0, v5, v6, 2 bitop3:0x36
	v_lshl_or_b32 v93, v0, 4, v4
	v_bitop3_b32 v0, v5, v6, 4 bitop3:0x36
	v_lshl_or_b32 v94, v0, 4, v4
	v_bitop3_b32 v0, v5, v6, 6 bitop3:0x36
	v_lshl_or_b32 v95, v0, 4, v4
	v_bitop3_b32 v0, v5, v6, 8 bitop3:0x36
	v_lshl_or_b32 v96, v0, 4, v4
	v_bitop3_b32 v0, v5, v6, 10 bitop3:0x36
	v_lshl_or_b32 v97, v0, 4, v4
	v_bitop3_b32 v0, v5, v6, 12 bitop3:0x36
	s_add_u32 s42, s1, 0x15401000
	v_bitop3_b32 v9, v5, v2, 15 bitop3:0x78
	v_lshl_or_b32 v155, v0, 4, v4
	v_bitop3_b32 v0, v5, v6, 14 bitop3:0x36
	s_mov_b32 m0, s68
	s_addc_u32 s43, s12, 0
	v_lshl_or_b32 v92, v9, 4, v4
	v_lshl_or_b32 v156, v0, 4, v4
	s_waitcnt lgkmcnt(0)
	s_barrier
	v_and_b32_e32 v1, 12, v3
	global_load_lds_dwordx4 v165, s[42:43]
	s_mov_b32 m0, s46
	v_lshlrev_b32_e32 v3, 1, v2
	global_load_lds_dwordx4 v166, s[42:43]
	v_and_b32_e32 v3, 32, v3
	v_lshlrev_b32_e32 v35, 3, v32
	v_bfe_u32 v0, v2, 2, 2
	v_add_u32_e32 v3, v3, v7
	v_and_b32_e32 v34, 24, v35
	v_or3_b32 v0, v0, v1, v3
	v_lshl_or_b32 v0, v0, 12, v34
	s_add_u32 s2, s1, 0x15401400
	v_readfirstlane_b32 s1, v2
	v_and_or_b32 v1, v2, 32, v0
	s_waitcnt vmcnt(0)
	s_addc_u32 s3, s12, 0
	v_lshlrev_b32_e32 v146, 1, v1
	v_lshrrev_b32_e32 v1, 4, v8
	s_waitcnt lgkmcnt(0)
	s_barrier
	s_and_b32 s12, s1, 0xffffff00
	v_and_or_b32 v0, v1, s27, v0
	s_cmpk_eq_i32 s12, 0x100
	v_lshlrev_b32_e32 v144, 1, v0
	s_cselect_b64 s[4:5], -1, 0
	s_cmpk_lg_i32 s12, 0x100
	s_waitcnt vmcnt(0)
	s_cbranch_scc1 .LBB0_1916
	s_add_u32 s20, s42, 0x80000
	s_addc_u32 s21, s43, 0
	s_mov_b32 m0, s47
	s_nop 0
	global_load_lds_dwordx4 v165, s[20:21]
	s_mov_b32 m0, s48
	s_nop 0
	global_load_lds_dwordx4 v166, s[20:21]
	s_mov_b32 m0, s49
	s_nop 0
	global_load_lds_dwordx4 v146, s[2:3]
	s_mov_b32 m0, s50
	s_nop 0
	global_load_lds_dwordx4 v144, s[2:3]
	s_waitcnt lgkmcnt(0)
	s_barrier

.LBB0_2578:
	s_and_b64 s[0:1], s[4:5], exec
	s_cselect_b32 s1, s86, s87
	s_lshl_b32 s0, s1, 8
	s_or_b32 s52, s38, s0
	s_mul_hi_u32 s3, s52, 0x1200
	s_mul_i32 s6, s39, 0x1200
	s_mul_i32 s2, s52, 0x1200
	s_add_i32 s3, s3, s6
	v_mbcnt_lo_u32_b32 v0, -1, 0
	v_mbcnt_hi_u32_b32 v0, -1, v0
	s_add_u32 s2, s88, s2
	v_or_b32_e32 v4, s33, v0
	s_addc_u32 s3, s16, s3
	v_ashrrev_i32_e32 v5, 6, v4
	v_and_b32_e32 v32, 31, v4
	v_lshlrev_b32_e32 v33, 5, v5
	v_bfe_u32 v6, v4, 5, 1
	v_or_b32_e32 v0, v33, v32
	v_mov_b64_e32 v[2:3], s[2:3]
	s_movk_i32 s2, 0x1200
	v_and_b32_e32 v34, 63, v4
	v_mad_i64_i32 v[2:3], s[2:3], v0, s2, v[2:3]
	v_lshlrev_b32_e32 v0, 4, v6
	v_lshl_add_u64 v[2:3], v[2:3], 0, v[0:1]
	v_lshlrev_b32_e32 v0, 11, v5
	v_lshlrev_b32_e32 v35, 4, v34
	v_or_b32_e32 v9, v35, v0
	v_ashrrev_i32_e32 v9, 8, v9
	v_lshlrev_b32_e32 v7, 2, v5
	v_xor_b32_e32 v10, v9, v4
	v_and_b32_e32 v11, 3, v9
	v_lshrrev_b32_e32 v9, 1, v9
	v_and_b32_e32 v8, 0x7ffffff0, v7
	v_and_b32_e32 v9, 12, v9
	v_or3_b32 v9, v11, v9, v8
	v_mul_lo_u32 v9, v9, s69
	v_lshlrev_b32_e32 v10, 3, v10
	v_and_or_b32 v9, v10, s70, v9
	v_lshlrev_b32_e32 v184, 1, v9
	v_or_b32_e32 v9, 0x400, v35
	v_or_b32_e32 v0, v9, v0
	v_ashrrev_i32_e32 v0, 8, v0
	v_xor_b32_e32 v10, v0, v4
	v_and_b32_e32 v11, 3, v0
	v_lshrrev_b32_e32 v0, 1, v0
	v_and_b32_e32 v0, 12, v0
	v_or3_b32 v0, v11, v0, v8
	v_mul_lo_u32 v0, v0, s69
	v_lshlrev_b32_e32 v10, 3, v10
	v_and_or_b32 v0, v10, s70, v0
	v_lshl_add_u32 v185, v0, 1, v176
	v_lshl_or_b32 v0, v5, 10, v35
	v_ashrrev_i32_e32 v5, 7, v0
	v_lshrrev_b32_e32 v0, 8, v0
	v_and_b32_e32 v10, 3, v5
	v_lshrrev_b32_e32 v11, 1, v5
	v_lshlrev_b32_e32 v5, 3, v5
	v_xor_b32_e32 v0, v0, v4
	v_and_b32_e32 v5, 32, v5
	v_and_b32_e32 v11, 12, v11
	v_add_u32_e32 v5, v5, v8
	v_lshlrev_b32_e32 v0, 4, v0
	v_or3_b32 v5, v10, v11, v5
	v_and_b32_e32 v0, 0x70, v0
	v_lshl_or_b32 v186, v5, 7, v0
	v_and_b32_e32 v0, 15, v4
	v_lshlrev_b32_e32 v12, 8, v32
	global_load_dwordx4 v[172:175], v[2:3], off
	global_load_dwordx4 v[168:171], v[2:3], off offset:32
	global_load_dwordx4 v[164:167], v[2:3], off offset:64
	global_load_dwordx4 v[160:163], v[2:3], off offset:96
	global_load_dwordx4 v[156:159], v[2:3], off offset:128
	global_load_dwordx4 v[152:155], v[2:3], off offset:160
	global_load_dwordx4 v[148:151], v[2:3], off offset:192
	global_load_dwordx4 v[144:147], v[2:3], off offset:224
	global_load_dwordx4 v[140:143], v[2:3], off offset:256
	global_load_dwordx4 v[136:139], v[2:3], off offset:288
	global_load_dwordx4 v[132:135], v[2:3], off offset:320
	global_load_dwordx4 v[128:131], v[2:3], off offset:352
	v_bitop3_b32 v2, v6, v0, 2 bitop3:0x36
	v_lshl_or_b32 v200, v2, 4, v12
	v_bitop3_b32 v2, v6, v0, 4 bitop3:0x36
	v_lshl_or_b32 v201, v2, 4, v12
	v_bitop3_b32 v2, v6, v0, 6 bitop3:0x36
	v_lshl_or_b32 v202, v2, 4, v12
	v_bitop3_b32 v2, v6, v0, 8 bitop3:0x36
	v_lshl_or_b32 v197, v2, 4, v12
	v_bitop3_b32 v2, v6, v0, 10 bitop3:0x36
	v_lshrrev_b32_e32 v5, 1, v4
	v_lshl_or_b32 v198, v2, 4, v12
	v_bitop3_b32 v2, v6, v0, 12 bitop3:0x36
	v_bitop3_b32 v0, v6, v0, 14 bitop3:0x36
	v_bfe_u32 v10, v4, 1, 3
	v_lshl_or_b32 v11, v32, 7, v177
	v_lshl_or_b32 v196, v0, 4, v12
	v_bitop3_b32 v0, v6, v5, 7 bitop3:0x78
	v_lshl_or_b32 v192, v0, 4, v11
	v_bitop3_b32 v0, v6, v10, 2 bitop3:0x36
	v_lshl_or_b32 v193, v0, 4, v11
	v_bitop3_b32 v0, v6, v10, 4 bitop3:0x36
	v_bitop3_b32 v13, v6, v4, 15 bitop3:0x78
	v_lshl_or_b32 v190, v0, 4, v11
	v_bitop3_b32 v0, v6, v10, 6 bitop3:0x36
	s_mov_b32 m0, s64
	v_lshl_or_b32 v199, v13, 4, v12
	v_lshl_or_b32 v195, v2, 4, v12
	v_lshl_or_b32 v191, v0, 4, v11
	v_readfirstlane_b32 s3, v179
	v_readfirstlane_b32 s2, v180
	s_waitcnt lgkmcnt(0)
	s_barrier
	v_lshlrev_b32_e32 v3, 1, v4
	s_nop 2
	global_load_lds_dwordx4 v184, s[2:3]
	s_mov_b32 m0, s84
	v_and_b32_e32 v3, 32, v3
	global_load_lds_dwordx4 v185, s[2:3]
	v_readfirstlane_b32 s3, v181
	v_readfirstlane_b32 s2, v182
	s_add_i32 m0, s67, 0x4000
	v_bfe_u32 v0, v4, 2, 2
	v_and_b32_e32 v2, 12, v7
	v_add_u32_e32 v3, v3, v8
	s_nop 0
	global_load_lds_dwordx4 v186, s[2:3]
	v_lshlrev_b32_e32 v37, 3, v34
	v_or3_b32 v0, v0, v2, v3
	v_and_b32_e32 v36, 24, v37
	v_mul_lo_u32 v0, v0, s69
	v_or_b32_e32 v0, v0, v36
	v_and_b32_e32 v187, 32, v4
	v_or_b32_e32 v2, v0, v187
	v_readfirstlane_b32 s2, v4
	v_lshlrev_b32_e32 v189, 1, v2
	v_lshrrev_b32_e32 v2, 4, v9
	s_movk_i32 s3, 0x60
	s_waitcnt vmcnt(0)
	v_and_or_b32 v0, v2, s3, v0
	s_waitcnt lgkmcnt(0)
	s_barrier
	s_and_b32 s3, s2, 0xffffff00
	s_cmpk_eq_i32 s3, 0x100
	v_lshlrev_b32_e32 v188, 1, v0
	s_cselect_b64 s[56:57], -1, 0
	s_cmpk_lg_i32 s3, 0x100
	s_waitcnt vmcnt(0)
	s_cbranch_scc1 .LBB0_2580
	s_mov_b32 m0, s71
	s_nop 0
	global_load_lds_dwordx4 v184, s[42:43]
	s_mov_b32 m0, s72
	s_nop 0
	global_load_lds_dwordx4 v185, s[42:43]
	s_mov_b32 m0, s73
	s_nop 0
	global_load_lds_dwordx4 v186, s[44:45]
	s_mov_b32 m0, s74
	s_nop 0
	global_load_lds_dwordx4 v189, s[40:41]
	s_mov_b32 m0, s75
	s_nop 0
	global_load_lds_dwordx4 v188, s[40:41]
	s_waitcnt lgkmcnt(0)
	s_barrier

.LBB0_2650:
	s_ashr_i32 s0, s81, 5
	s_ashr_i32 s1, s0, 31
	s_lshl_b64 s[6:7], s[0:1], 11
	s_and_b32 s1, s24, 0x700
	s_or_b32 s6, s6, s1
	s_mul_i32 s1, s7, 0xe00
	s_mul_hi_u32 s2, s6, 0xe00
	s_add_i32 s2, s2, s1
	s_mul_i32 s1, s6, 0xe00
	s_add_u32 s1, s30, s1
	s_addc_u32 s3, s31, s2
	s_and_b32 s2, s16, 0x180
	s_lshl_b32 s47, s2, 1
	s_add_u32 s2, s1, s47
	s_addc_u32 s3, s3, 0
	s_lshl_b32 s0, s0, 8
	s_ashr_i32 s1, s0, 31
	s_lshl_b64 s[0:1], s[0:1], 13
	s_add_u32 s0, s22, s0
	v_mbcnt_lo_u32_b32 v0, -1, 0
	v_mbcnt_hi_u32_b32 v0, -1, v0
	s_addc_u32 s1, s23, s1
	v_or_b32_e32 v2, s33, v0
	s_add_u32 s4, s0, s47
	v_ashrrev_i32_e32 v3, 6, v2
	v_and_b32_e32 v4, 31, v2
	v_and_b32_e32 v32, 63, v2
	v_lshl_or_b32 v6, v3, 5, v4
	s_waitcnt lgkmcnt(0)
	v_mov_b64_e32 v[0:1], s[2:3]
	s_addc_u32 s5, s1, 0
	v_mad_i64_i32 v[0:1], s[0:1], v6, s26, v[0:1]
	v_lshlrev_b32_e32 v6, 11, v3
	v_lshlrev_b32_e32 v33, 4, v32
	v_or_b32_e32 v8, v33, v6
	v_ashrrev_i32_e32 v8, 8, v8
	v_lshlrev_b32_e32 v3, 2, v3
	v_xor_b32_e32 v9, v8, v2
	v_and_b32_e32 v10, 3, v8
	v_lshrrev_b32_e32 v8, 1, v8
	v_and_b32_e32 v7, 0x7ffffff0, v3
	v_and_b32_e32 v8, 12, v8
	v_lshlrev_b32_e32 v9, 4, v9
	v_or3_b32 v8, v10, v8, v7
	v_and_b32_e32 v9, 0xf0, v9
	v_lshl_or_b32 v165, v8, 13, v9
	v_or_b32_e32 v8, 0x400, v33
	v_or_b32_e32 v6, v8, v6
	v_ashrrev_i32_e32 v6, 8, v6
	v_xor_b32_e32 v9, v6, v2
	v_and_b32_e32 v10, 3, v6
	v_lshrrev_b32_e32 v6, 1, v6
	v_and_b32_e32 v6, 12, v6
	v_lshlrev_b32_e32 v9, 4, v9
	v_bfe_u32 v5, v2, 5, 1
	v_or3_b32 v6, v10, v6, v7
	v_and_b32_e32 v9, 0xf0, v9
	v_lshlrev_b32_e32 v144, 4, v5
	v_lshl_or_b32 v6, v6, 13, v9
	v_lshl_add_u64 v[0:1], v[0:1], 0, v[144:145]
	v_add_u32_e32 v166, 0x40000, v6
	v_and_b32_e32 v6, 15, v2
	v_lshlrev_b32_e32 v4, 8, v4
	global_load_dwordx4 v[140:143], v[0:1], off offset:1024
	global_load_dwordx4 v[136:139], v[0:1], off offset:1056
	global_load_dwordx4 v[132:135], v[0:1], off offset:1088
	global_load_dwordx4 v[128:131], v[0:1], off offset:1120
	global_load_dwordx4 v[124:127], v[0:1], off offset:1152
	global_load_dwordx4 v[120:123], v[0:1], off offset:1184
	global_load_dwordx4 v[116:119], v[0:1], off offset:1216
	global_load_dwordx4 v[112:115], v[0:1], off offset:1248
	v_bitop3_b32 v0, v5, v6, 2 bitop3:0x36
	v_lshl_or_b32 v93, v0, 4, v4
	v_bitop3_b32 v0, v5, v6, 4 bitop3:0x36
	v_lshl_or_b32 v94, v0, 4, v4
	v_bitop3_b32 v0, v5, v6, 6 bitop3:0x36
	v_lshl_or_b32 v95, v0, 4, v4
	v_bitop3_b32 v0, v5, v6, 8 bitop3:0x36
	v_lshl_or_b32 v96, v0, 4, v4
	v_bitop3_b32 v0, v5, v6, 10 bitop3:0x36
	v_lshl_or_b32 v97, v0, 4, v4
	v_bitop3_b32 v0, v5, v6, 12 bitop3:0x36
	s_add_u32 s8, s4, 0x15401800
	v_bitop3_b32 v9, v5, v2, 15 bitop3:0x78
	v_lshl_or_b32 v155, v0, 4, v4
	v_bitop3_b32 v0, v5, v6, 14 bitop3:0x36
	s_mov_b32 m0, s64
	s_addc_u32 s9, s5, 0
	v_lshl_or_b32 v92, v9, 4, v4
	v_lshl_or_b32 v156, v0, 4, v4
	s_waitcnt lgkmcnt(0)
	s_barrier
	v_and_b32_e32 v1, 12, v3
	global_load_lds_dwordx4 v165, s[8:9]
	s_mov_b32 m0, s36
	v_lshlrev_b32_e32 v3, 1, v2
	global_load_lds_dwordx4 v166, s[8:9]
	v_and_b32_e32 v3, 32, v3
	v_lshlrev_b32_e32 v35, 3, v32
	v_bfe_u32 v0, v2, 2, 2
	v_add_u32_e32 v3, v3, v7
	v_and_b32_e32 v34, 24, v35
	v_or3_b32 v0, v0, v1, v3
	v_lshl_or_b32 v0, v0, 12, v34
	s_add_u32 s2, s4, 0x15401c00
	v_readfirstlane_b32 s0, v2
	v_and_or_b32 v1, v2, 32, v0
	s_waitcnt vmcnt(0)
	s_addc_u32 s3, s5, 0
	v_lshlrev_b32_e32 v146, 1, v1
	v_lshrrev_b32_e32 v1, 4, v8
	s_waitcnt lgkmcnt(0)
	s_barrier
	s_and_b32 s1, s0, 0xffffff00
	v_and_or_b32 v0, v1, s27, v0
	s_cmpk_eq_i32 s1, 0x100
	v_lshlrev_b32_e32 v144, 1, v0
	s_cselect_b64 s[4:5], -1, 0
	s_cmpk_lg_i32 s1, 0x100
	s_waitcnt vmcnt(0)
	s_cbranch_scc1 .LBB0_2652
	s_add_u32 s20, s8, 0x80000
	s_addc_u32 s21, s9, 0
	s_mov_b32 m0, s37
	s_nop 0
	global_load_lds_dwordx4 v165, s[20:21]
	s_mov_b32 m0, s38
	s_nop 0
	global_load_lds_dwordx4 v166, s[20:21]
	s_mov_b32 m0, s39
	s_nop 0
	global_load_lds_dwordx4 v146, s[2:3]
	s_mov_b32 m0, s40
	s_nop 0
	global_load_lds_dwordx4 v144, s[2:3]
	s_waitcnt lgkmcnt(0)
	s_barrier
